# P1 spare-workgroup copy share 22% -> 27.5% (group-wise scalar-addressed double-buffered copy loop), P5 18%, P7 54.5%
# baseline (speedup 1.0000x reference)
.LBB0_44:
	s_or_b64 exec, exec, s[2:3]
	s_cmpk_lt_i32 s26, 0x80
	s_cselect_b64 s[0:1], -1, 0
	s_add_u32 s70, s22, 0x6580000
	s_mul_i32 s2, s92, 0x600
	s_addc_u32 s71, s23, 0
	v_add_u32_e32 v1, s2, v2
	s_mov_b32 s2, 0x230000
	s_add_u32 s66, s22, 0xe580000
	v_cmp_gt_i32_e32 vcc, s2, v1
	s_addc_u32 s67, s23, 0
	s_lshl_b32 s63, s26, 11
	s_and_b64 s[2:3], s[0:1], vcc
	s_and_saveexec_b64 s[0:1], s[2:3]
	s_cbranch_execz .LBB0_47
	s_mov_b64 s[2:3], 0
	s_mov_b32 s4, 0x80808081
	s_mov_b32 s5, 0xfffc0400
	s_movk_i32 s10, 0x4000
	s_mov_b32 s11, 0x22ffff
.LBB0_46:
	v_mul_hi_i32 v2, v1, s4
	v_min_i32_e32 v3, 0x22fdff, v1
	v_min_i32_e32 v4, 0x22fbff, v1
	v_min_i32_e32 v5, 0x22f9ff, v1
	v_add_u32_e32 v2, v2, v1
	v_add_u32_e32 v7, 0x200, v3
	v_add_u32_e32 v9, 0x400, v4
	v_add_u32_e32 v11, 0x600, v5
	v_lshrrev_b32_e32 v3, 31, v2
	v_ashrrev_i32_e32 v2, 17, v2
	v_mul_hi_i32 v4, v7, s4
	v_mul_hi_i32 v5, v9, s4
	v_mul_hi_i32 v6, v11, s4
	v_add_u32_e32 v2, v2, v3
	v_add_u32_e32 v8, v4, v7
	v_add_u32_e32 v5, v5, v9
	v_add_u32_e32 v6, v6, v11
	v_mad_i32_i24 v4, v2, s5, v1
	v_ashrrev_i32_e32 v3, 31, v2
	v_lshrrev_b32_e32 v10, 31, v8
	v_ashrrev_i32_e32 v8, 17, v8
	v_lshrrev_b32_e32 v12, 31, v5
	v_ashrrev_i32_e32 v13, 17, v5
	v_lshrrev_b32_e32 v14, 31, v6
	v_ashrrev_i32_e32 v15, 17, v6
	v_lshlrev_b64 v[2:3], 18, v[2:3]
	v_ashrrev_i32_e32 v5, 31, v4
	v_add_u32_e32 v6, v8, v10
	v_add_u32_e32 v8, v13, v12
	v_add_u32_e32 v10, v15, v14
	v_lshl_add_u64 v[2:3], v[2:3], 0, v[4:5]
	v_mad_i32_i24 v4, v6, s5, v7
	v_ashrrev_i32_e32 v7, 31, v6
	v_mad_i32_i24 v12, v8, s5, v9
	v_ashrrev_i32_e32 v9, 31, v8
	v_mad_i32_i24 v14, v10, s5, v11
	v_ashrrev_i32_e32 v11, 31, v10
	v_lshlrev_b64 v[34:35], 4, v[2:3]
	v_lshlrev_b64 v[2:3], 18, v[6:7]
	v_ashrrev_i32_e32 v5, 31, v4
	v_lshlrev_b64 v[6:7], 18, v[8:9]
	v_ashrrev_i32_e32 v13, 31, v12
	v_lshlrev_b64 v[8:9], 18, v[10:11]
	v_ashrrev_i32_e32 v15, 31, v14
	s_waitcnt lgkmcnt(0)
	v_lshl_add_u64 v[10:11], s[82:83], 0, v[34:35]
	v_lshl_add_u64 v[2:3], v[2:3], 0, v[4:5]
	v_lshl_add_u64 v[4:5], v[6:7], 0, v[12:13]
	v_lshl_add_u64 v[6:7], v[8:9], 0, v[14:15]
	v_add_co_u32_e32 v8, vcc, s10, v10
	v_lshl_add_u64 v[16:17], s[84:85], 0, v[34:35]
	s_nop 0
	v_addc_co_u32_e32 v9, vcc, 0, v11, vcc
	v_lshlrev_b64 v[36:37], 4, v[2:3]
	v_lshlrev_b64 v[40:41], 4, v[6:7]
	v_add_co_u32_e32 v6, vcc, s10, v16
	v_lshl_add_u64 v[10:11], s[82:83], 0, v[36:37]
	s_nop 0
	v_addc_co_u32_e32 v7, vcc, 0, v17, vcc
	v_add_co_u32_e32 v10, vcc, s10, v10
	v_lshl_add_u64 v[12:13], s[84:85], 0, v[36:37]
	s_nop 0
	v_addc_co_u32_e32 v11, vcc, 0, v11, vcc
	v_lshlrev_b64 v[38:39], 4, v[4:5]
	v_add_co_u32_e32 v16, vcc, s10, v12
	v_lshl_add_u64 v[14:15], s[82:83], 0, v[38:39]
	s_nop 0
	v_addc_co_u32_e32 v17, vcc, 0, v13, vcc
	v_add_co_u32_e32 v24, vcc, s10, v14
	v_lshl_add_u64 v[18:19], s[84:85], 0, v[38:39]
	s_nop 0
	v_addc_co_u32_e32 v25, vcc, 0, v15, vcc
	v_add_co_u32_e32 v26, vcc, s10, v18
	v_lshl_add_u64 v[20:21], s[82:83], 0, v[40:41]
	s_nop 0
	v_addc_co_u32_e32 v27, vcc, 0, v19, vcc
	v_add_co_u32_e32 v28, vcc, s10, v20
	v_lshl_add_u64 v[22:23], s[84:85], 0, v[40:41]
	s_nop 0
	v_addc_co_u32_e32 v29, vcc, 0, v21, vcc
	v_add_co_u32_e32 v30, vcc, s10, v22
	global_load_dwordx4 v[2:5], v[8:9], off nt
	s_nop 0
	v_addc_co_u32_e32 v31, vcc, 0, v23, vcc
	global_load_dwordx4 v[6:9], v[6:7], off nt
	s_nop 0
	global_load_dwordx4 v[10:13], v[10:11], off nt
	s_nop 0
	global_load_dwordx4 v[14:17], v[16:17], off nt
	s_nop 0
	global_load_dwordx4 v[18:21], v[24:25], off nt
	s_nop 0
	global_load_dwordx4 v[22:25], v[26:27], off nt
	s_nop 0
	global_load_dwordx4 v[26:29], v[28:29], off nt
	s_nop 0
	global_load_dwordx4 v[30:33], v[30:31], off nt
	v_add_u32_e32 v1, s63, v1
	v_cmp_lt_i32_e32 vcc, s11, v1
	s_or_b64 s[2:3], vcc, s[2:3]
	v_lshl_add_u64 v[42:43], s[70:71], 0, v[34:35]
	v_lshl_add_u64 v[34:35], s[66:67], 0, v[34:35]
	v_lshl_add_u64 v[44:45], s[70:71], 0, v[36:37]
	v_lshl_add_u64 v[36:37], s[66:67], 0, v[36:37]
	v_lshl_add_u64 v[46:47], s[70:71], 0, v[38:39]
	v_lshl_add_u64 v[38:39], s[66:67], 0, v[38:39]
	v_lshl_add_u64 v[48:49], s[70:71], 0, v[40:41]
	v_lshl_add_u64 v[40:41], s[66:67], 0, v[40:41]
	s_waitcnt vmcnt(7)
	global_store_dwordx4 v[42:43], v[2:5], off nt
	s_waitcnt vmcnt(7)
	global_store_dwordx4 v[34:35], v[6:9], off nt
	s_waitcnt vmcnt(7)
	global_store_dwordx4 v[44:45], v[10:13], off nt
	s_waitcnt vmcnt(7)
	global_store_dwordx4 v[36:37], v[14:17], off nt
	s_waitcnt vmcnt(7)
	global_store_dwordx4 v[46:47], v[18:21], off nt
	s_waitcnt vmcnt(7)
	global_store_dwordx4 v[38:39], v[22:25], off nt
	s_waitcnt vmcnt(7)
	global_store_dwordx4 v[48:49], v[26:29], off nt
	s_waitcnt vmcnt(7)
	global_store_dwordx4 v[40:41], v[30:33], off nt
	s_andn2_b64 exec, exec, s[2:3]
	s_cbranch_execnz .LBB0_46

.LBB0_111:
	v_writelane_b32 v247, s68, 13
	s_nop 1
	v_writelane_b32 v247, s69, 14
	v_writelane_b32 v247, s63, 15
	v_writelane_b32 v247, s64, 16
	s_nop 1
	v_writelane_b32 v247, s65, 17
	s_or_b64 exec, exec, s[0:1]
	s_add_u32 s68, s24, 0x4200000
	s_addc_u32 s69, s25, 0
	s_sub_i32 s0, s26, 28
	s_cmpk_gt_i32 s26, 0x7f
	s_cselect_b32 s33, s0, s26
	s_ashr_i32 s93, s92, 31
	s_lshr_b32 s0, s93, 29
	s_add_i32 s2, s92, s0
	s_and_b32 s0, s2, -8
	s_sub_i32 s0, s92, s0
	s_cmp_lt_i32 s0, 6
	v_writelane_b32 v247, s0, 18
	s_cselect_b64 s[0:1], -1, 0
	v_writelane_b32 v247, s0, 19
	s_ashr_i32 s44, s33, 31
	s_cmp_ge_i32 s92, s33
	v_writelane_b32 v247, s1, 20
	s_mov_b64 s[0:1], -1
	s_waitcnt lgkmcnt(0)
	s_barrier
	s_cbranch_scc0 .LBB0_117
	s_sub_i32 s0, s92, s33
	s_mul_i32 s1, s0, 16
	s_add_i32 s3, s1, 16
	v_lshlrev_b32_e32 v224, 4, v222
	v_add_u32_e32 v225, 0x2000, v224
	v_add_u32_e32 v226, 0x4000, v224
	v_add_u32_e32 v227, 0x6000, v224
	v_add_u32_e32 v228, 0x8000, v224
	v_add_u32_e32 v229, 0xa000, v224
	v_add_u32_e32 v230, 0xc000, v224
	v_add_u32_e32 v231, 0xe000, v224
	v_add_u32_e32 v232, 0x10000, v224
	v_add_u32_e32 v233, 0x12000, v224
	s_mul_i32 s4, s1, 0x5051
	s_lshr_b32 s4, s4, 20
	s_mul_i32 s5, s4, 51
	s_sub_i32 s5, s1, s5
	s_mul_i32 s5, s5, 0x14000
	s_lshl_b32 s4, s4, 22
	s_add_u32 s4, s4, s5
	s_add_u32 s60, s82, s4
	s_addc_u32 s61, s83, 0
	s_add_u32 s60, s60, 0x4000
	s_addc_u32 s61, s61, 0
	s_add_u32 s62, s84, s4
	s_addc_u32 s63, s85, 0
	s_add_u32 s62, s62, 0x4000
	s_addc_u32 s63, s63, 0
	s_add_u32 s64, s70, s4
	s_addc_u32 s65, s71, 0
	s_add_u32 s72, s66, s4
	s_addc_u32 s73, s67, 0
	global_load_dwordx4 v[0:3], v224, s[60:61] nt
	global_load_dwordx4 v[4:7], v224, s[62:63] nt
	global_load_dwordx4 v[8:11], v225, s[60:61] nt
	global_load_dwordx4 v[12:15], v225, s[62:63] nt
	global_load_dwordx4 v[16:19], v226, s[60:61] nt
	global_load_dwordx4 v[20:23], v226, s[62:63] nt
	global_load_dwordx4 v[24:27], v227, s[60:61] nt
	global_load_dwordx4 v[28:31], v227, s[62:63] nt
	global_load_dwordx4 v[32:35], v228, s[60:61] nt
	global_load_dwordx4 v[36:39], v228, s[62:63] nt
	global_load_dwordx4 v[40:43], v229, s[60:61] nt
	global_load_dwordx4 v[44:47], v229, s[62:63] nt
	global_load_dwordx4 v[60:63], v230, s[60:61] nt
	global_load_dwordx4 v[64:67], v230, s[62:63] nt
	global_load_dwordx4 v[68:71], v231, s[60:61] nt
	global_load_dwordx4 v[72:75], v231, s[62:63] nt
	global_load_dwordx4 v[76:79], v232, s[60:61] nt
	global_load_dwordx4 v[80:83], v232, s[62:63] nt
	global_load_dwordx4 v[84:87], v233, s[60:61] nt
	global_load_dwordx4 v[88:91], v233, s[62:63] nt
	s_add_i32 s7, s1, 1
	s_mul_i32 s4, s7, 0x5051
	s_lshr_b32 s4, s4, 20
	s_mul_i32 s5, s4, 51
	s_sub_i32 s5, s7, s5
	s_mul_i32 s5, s5, 0x14000
	s_lshl_b32 s4, s4, 22
	s_add_u32 s4, s4, s5
	s_add_u32 s74, s82, s4
	s_addc_u32 s75, s83, 0
	s_add_u32 s74, s74, 0x4000
	s_addc_u32 s75, s75, 0
	s_add_u32 s88, s84, s4
	s_addc_u32 s89, s85, 0
	s_add_u32 s88, s88, 0x4000
	s_addc_u32 s89, s89, 0
	s_add_u32 s90, s70, s4
	s_addc_u32 s91, s71, 0
	s_add_u32 s94, s66, s4
	s_addc_u32 s95, s67, 0
	global_load_dwordx4 v[92:95], v224, s[74:75] nt
	global_load_dwordx4 v[100:103], v224, s[88:89] nt
	global_load_dwordx4 v[108:111], v225, s[74:75] nt
	global_load_dwordx4 v[112:115], v225, s[88:89] nt
	global_load_dwordx4 v[116:119], v226, s[74:75] nt
	global_load_dwordx4 v[120:123], v226, s[88:89] nt
	global_load_dwordx4 v[124:127], v227, s[74:75] nt
	global_load_dwordx4 v[128:131], v227, s[88:89] nt
	global_load_dwordx4 v[132:135], v228, s[74:75] nt
	global_load_dwordx4 v[136:139], v228, s[88:89] nt
	global_load_dwordx4 v[140:143], v229, s[74:75] nt
	global_load_dwordx4 v[152:155], v229, s[88:89] nt
	global_load_dwordx4 v[156:159], v230, s[74:75] nt
	global_load_dwordx4 v[160:163], v230, s[88:89] nt
	global_load_dwordx4 v[164:167], v231, s[74:75] nt
	global_load_dwordx4 v[168:171], v231, s[88:89] nt
	global_load_dwordx4 v[172:175], v232, s[74:75] nt
	global_load_dwordx4 v[176:179], v232, s[88:89] nt
	global_load_dwordx4 v[180:183], v233, s[74:75] nt
	global_load_dwordx4 v[184:187], v233, s[88:89] nt
	s_waitcnt vmcnt(20)
	global_store_dwordx4 v224, v[0:3], s[64:65] nt
	global_store_dwordx4 v224, v[4:7], s[72:73] nt
	global_store_dwordx4 v225, v[8:11], s[64:65] nt
	global_store_dwordx4 v225, v[12:15], s[72:73] nt
	global_store_dwordx4 v226, v[16:19], s[64:65] nt
	global_store_dwordx4 v226, v[20:23], s[72:73] nt
	global_store_dwordx4 v227, v[24:27], s[64:65] nt
	global_store_dwordx4 v227, v[28:31], s[72:73] nt
	global_store_dwordx4 v228, v[32:35], s[64:65] nt
	global_store_dwordx4 v228, v[36:39], s[72:73] nt
	global_store_dwordx4 v229, v[40:43], s[64:65] nt
	global_store_dwordx4 v229, v[44:47], s[72:73] nt
	global_store_dwordx4 v230, v[60:63], s[64:65] nt
	global_store_dwordx4 v230, v[64:67], s[72:73] nt
	global_store_dwordx4 v231, v[68:71], s[64:65] nt
	global_store_dwordx4 v231, v[72:75], s[72:73] nt
	global_store_dwordx4 v232, v[76:79], s[64:65] nt
	global_store_dwordx4 v232, v[80:83], s[72:73] nt
	global_store_dwordx4 v233, v[84:87], s[64:65] nt
	global_store_dwordx4 v233, v[88:91], s[72:73] nt
	s_add_i32 s1, s1, 2
.Lcp1_top:
	s_cmp_ge_u32 s1, s3
	s_cbranch_scc1 .Lcp1_drain
	s_mul_i32 s4, s1, 0x5051
	s_lshr_b32 s4, s4, 20
	s_mul_i32 s5, s4, 51
	s_sub_i32 s5, s1, s5
	s_mul_i32 s5, s5, 0x14000
	s_lshl_b32 s4, s4, 22
	s_add_u32 s4, s4, s5
	s_add_u32 s60, s82, s4
	s_addc_u32 s61, s83, 0
	s_add_u32 s60, s60, 0x4000
	s_addc_u32 s61, s61, 0
	s_add_u32 s62, s84, s4
	s_addc_u32 s63, s85, 0
	s_add_u32 s62, s62, 0x4000
	s_addc_u32 s63, s63, 0
	s_add_u32 s64, s70, s4
	s_addc_u32 s65, s71, 0
	s_add_u32 s72, s66, s4
	s_addc_u32 s73, s67, 0
	global_load_dwordx4 v[0:3], v224, s[60:61] nt
	global_load_dwordx4 v[4:7], v224, s[62:63] nt
	global_load_dwordx4 v[8:11], v225, s[60:61] nt
	global_load_dwordx4 v[12:15], v225, s[62:63] nt
	global_load_dwordx4 v[16:19], v226, s[60:61] nt
	global_load_dwordx4 v[20:23], v226, s[62:63] nt
	global_load_dwordx4 v[24:27], v227, s[60:61] nt
	global_load_dwordx4 v[28:31], v227, s[62:63] nt
	global_load_dwordx4 v[32:35], v228, s[60:61] nt
	global_load_dwordx4 v[36:39], v228, s[62:63] nt
	global_load_dwordx4 v[40:43], v229, s[60:61] nt
	global_load_dwordx4 v[44:47], v229, s[62:63] nt
	global_load_dwordx4 v[60:63], v230, s[60:61] nt
	global_load_dwordx4 v[64:67], v230, s[62:63] nt
	global_load_dwordx4 v[68:71], v231, s[60:61] nt
	global_load_dwordx4 v[72:75], v231, s[62:63] nt
	global_load_dwordx4 v[76:79], v232, s[60:61] nt
	global_load_dwordx4 v[80:83], v232, s[62:63] nt
	global_load_dwordx4 v[84:87], v233, s[60:61] nt
	global_load_dwordx4 v[88:91], v233, s[62:63] nt
	s_waitcnt vmcnt(40)
	global_store_dwordx4 v224, v[92:95], s[90:91] nt
	global_store_dwordx4 v224, v[100:103], s[94:95] nt
	global_store_dwordx4 v225, v[108:111], s[90:91] nt
	global_store_dwordx4 v225, v[112:115], s[94:95] nt
	global_store_dwordx4 v226, v[116:119], s[90:91] nt
	global_store_dwordx4 v226, v[120:123], s[94:95] nt
	global_store_dwordx4 v227, v[124:127], s[90:91] nt
	global_store_dwordx4 v227, v[128:131], s[94:95] nt
	global_store_dwordx4 v228, v[132:135], s[90:91] nt
	global_store_dwordx4 v228, v[136:139], s[94:95] nt
	global_store_dwordx4 v229, v[140:143], s[90:91] nt
	global_store_dwordx4 v229, v[152:155], s[94:95] nt
	global_store_dwordx4 v230, v[156:159], s[90:91] nt
	global_store_dwordx4 v230, v[160:163], s[94:95] nt
	global_store_dwordx4 v231, v[164:167], s[90:91] nt
	global_store_dwordx4 v231, v[168:171], s[94:95] nt
	global_store_dwordx4 v232, v[172:175], s[90:91] nt
	global_store_dwordx4 v232, v[176:179], s[94:95] nt
	global_store_dwordx4 v233, v[180:183], s[90:91] nt
	global_store_dwordx4 v233, v[184:187], s[94:95] nt
	s_add_i32 s7, s1, 1
	s_mul_i32 s4, s7, 0x5051
	s_lshr_b32 s4, s4, 20
	s_mul_i32 s5, s4, 51
	s_sub_i32 s5, s7, s5
	s_mul_i32 s5, s5, 0x14000
	s_lshl_b32 s4, s4, 22
	s_add_u32 s4, s4, s5
	s_add_u32 s74, s82, s4
	s_addc_u32 s75, s83, 0
	s_add_u32 s74, s74, 0x4000
	s_addc_u32 s75, s75, 0
	s_add_u32 s88, s84, s4
	s_addc_u32 s89, s85, 0
	s_add_u32 s88, s88, 0x4000
	s_addc_u32 s89, s89, 0
	s_add_u32 s90, s70, s4
	s_addc_u32 s91, s71, 0
	s_add_u32 s94, s66, s4
	s_addc_u32 s95, s67, 0
	global_load_dwordx4 v[92:95], v224, s[74:75] nt
	global_load_dwordx4 v[100:103], v224, s[88:89] nt
	global_load_dwordx4 v[108:111], v225, s[74:75] nt
	global_load_dwordx4 v[112:115], v225, s[88:89] nt
	global_load_dwordx4 v[116:119], v226, s[74:75] nt
	global_load_dwordx4 v[120:123], v226, s[88:89] nt
	global_load_dwordx4 v[124:127], v227, s[74:75] nt
	global_load_dwordx4 v[128:131], v227, s[88:89] nt
	global_load_dwordx4 v[132:135], v228, s[74:75] nt
	global_load_dwordx4 v[136:139], v228, s[88:89] nt
	global_load_dwordx4 v[140:143], v229, s[74:75] nt
	global_load_dwordx4 v[152:155], v229, s[88:89] nt
	global_load_dwordx4 v[156:159], v230, s[74:75] nt
	global_load_dwordx4 v[160:163], v230, s[88:89] nt
	global_load_dwordx4 v[164:167], v231, s[74:75] nt
	global_load_dwordx4 v[168:171], v231, s[88:89] nt
	global_load_dwordx4 v[172:175], v232, s[74:75] nt
	global_load_dwordx4 v[176:179], v232, s[88:89] nt
	global_load_dwordx4 v[180:183], v233, s[74:75] nt
	global_load_dwordx4 v[184:187], v233, s[88:89] nt
	s_waitcnt vmcnt(40)
	global_store_dwordx4 v224, v[0:3], s[64:65] nt
	global_store_dwordx4 v224, v[4:7], s[72:73] nt
	global_store_dwordx4 v225, v[8:11], s[64:65] nt
	global_store_dwordx4 v225, v[12:15], s[72:73] nt
	global_store_dwordx4 v226, v[16:19], s[64:65] nt
	global_store_dwordx4 v226, v[20:23], s[72:73] nt
	global_store_dwordx4 v227, v[24:27], s[64:65] nt
	global_store_dwordx4 v227, v[28:31], s[72:73] nt
	global_store_dwordx4 v228, v[32:35], s[64:65] nt
	global_store_dwordx4 v228, v[36:39], s[72:73] nt
	global_store_dwordx4 v229, v[40:43], s[64:65] nt
	global_store_dwordx4 v229, v[44:47], s[72:73] nt
	global_store_dwordx4 v230, v[60:63], s[64:65] nt
	global_store_dwordx4 v230, v[64:67], s[72:73] nt
	global_store_dwordx4 v231, v[68:71], s[64:65] nt
	global_store_dwordx4 v231, v[72:75], s[72:73] nt
	global_store_dwordx4 v232, v[76:79], s[64:65] nt
	global_store_dwordx4 v232, v[80:83], s[72:73] nt
	global_store_dwordx4 v233, v[84:87], s[64:65] nt
	global_store_dwordx4 v233, v[88:91], s[72:73] nt
	s_add_i32 s1, s1, 2
	s_branch .Lcp1_top
.Lcp1_drain:
	s_waitcnt vmcnt(20)
	global_store_dwordx4 v224, v[92:95], s[90:91] nt
	global_store_dwordx4 v224, v[100:103], s[94:95] nt
	global_store_dwordx4 v225, v[108:111], s[90:91] nt
	global_store_dwordx4 v225, v[112:115], s[94:95] nt
	global_store_dwordx4 v226, v[116:119], s[90:91] nt
	global_store_dwordx4 v226, v[120:123], s[94:95] nt
	global_store_dwordx4 v227, v[124:127], s[90:91] nt
	global_store_dwordx4 v227, v[128:131], s[94:95] nt
	global_store_dwordx4 v228, v[132:135], s[90:91] nt
	global_store_dwordx4 v228, v[136:139], s[94:95] nt
	global_store_dwordx4 v229, v[140:143], s[90:91] nt
	global_store_dwordx4 v229, v[152:155], s[94:95] nt
	global_store_dwordx4 v230, v[156:159], s[90:91] nt
	global_store_dwordx4 v230, v[160:163], s[94:95] nt
	global_store_dwordx4 v231, v[164:167], s[90:91] nt
	global_store_dwordx4 v231, v[168:171], s[94:95] nt
	global_store_dwordx4 v232, v[172:175], s[90:91] nt
	global_store_dwordx4 v232, v[176:179], s[94:95] nt
	global_store_dwordx4 v233, v[180:183], s[90:91] nt
	global_store_dwordx4 v233, v[184:187], s[94:95] nt

.LBB0_661:
	s_lshl_b32 s64, s88, 11
	v_or_b32_e32 v0, s64, v222
	s_cmp_gt_i32 s88, 3
	v_add_u32_e32 v0, 0x22e000, v0
	s_mov_b32 s2, 0x39f800
	s_cselect_b64 s[0:1], -1, 0
	v_cmp_gt_i32_e32 vcc, s2, v0
	s_and_b64 s[2:3], s[0:1], vcc
	s_and_saveexec_b64 s[0:1], s[2:3]
	s_cbranch_execz .LBB0_664
	v_readlane_b32 s2, v247, 15
	v_add_u32_e32 v0, s64, v222
	s_add_i32 s6, s2, 0xffffe000
	v_add_u32_e32 v0, 0x22e000, v0
	s_mov_b64 s[2:3], 0
	s_mov_b32 s7, 0x80808081
	s_mov_b32 s8, 0xfffc0400
	s_movk_i32 s9, 0x4000
	s_mov_b32 s10, 0x39f7ff
.LBB0_663:
	s_waitcnt lgkmcnt(0)
	v_mul_hi_i32 v1, v0, s7
	v_min_i32_e32 v2, 0x39f5ff, v0
	v_min_i32_e32 v3, 0x39f3ff, v0
	v_min_i32_e32 v4, 0x39f1ff, v0
	v_add_u32_e32 v1, v1, v0
	v_add_u32_e32 v7, 0x200, v2
	v_add_u32_e32 v9, 0x400, v3
	v_add_u32_e32 v11, 0x600, v4
	v_lshrrev_b32_e32 v2, 31, v1
	v_ashrrev_i32_e32 v1, 17, v1
	v_mul_hi_i32 v3, v7, s7
	v_mul_hi_i32 v4, v9, s7
	v_mul_hi_i32 v5, v11, s7
	v_add_u32_e32 v2, v1, v2
	v_add_u32_e32 v1, v3, v7
	v_add_u32_e32 v6, v4, v9
	v_add_u32_e32 v5, v5, v11
	v_mad_i32_i24 v4, v2, s8, v0
	v_ashrrev_i32_e32 v3, 31, v2
	v_lshrrev_b32_e32 v8, 31, v1
	v_ashrrev_i32_e32 v1, 17, v1
	v_lshrrev_b32_e32 v10, 31, v6
	s_waitcnt vmcnt(9)
	v_ashrrev_i32_e32 v12, 17, v6
	v_lshrrev_b32_e32 v13, 31, v5
	v_ashrrev_i32_e32 v14, 17, v5
	v_lshlrev_b64 v[2:3], 18, v[2:3]
	v_ashrrev_i32_e32 v5, 31, v4
	v_add_u32_e32 v6, v1, v8
	v_add_u32_e32 v8, v12, v10
	v_add_u32_e32 v10, v14, v13
	v_lshl_add_u64 v[2:3], v[2:3], 0, v[4:5]
	v_mad_i32_i24 v4, v6, s8, v7
	v_ashrrev_i32_e32 v7, 31, v6
	v_mad_i32_i24 v12, v8, s8, v9
	v_ashrrev_i32_e32 v9, 31, v8
	v_mad_i32_i24 v14, v10, s8, v11
	v_ashrrev_i32_e32 v11, 31, v10
	s_waitcnt vmcnt(5)
	v_lshlrev_b64 v[34:35], 4, v[2:3]
	v_lshlrev_b64 v[2:3], 18, v[6:7]
	v_ashrrev_i32_e32 v5, 31, v4
	v_lshlrev_b64 v[6:7], 18, v[8:9]
	v_ashrrev_i32_e32 v13, 31, v12
	v_lshlrev_b64 v[8:9], 18, v[10:11]
	v_ashrrev_i32_e32 v15, 31, v14
	v_lshl_add_u64 v[10:11], s[82:83], 0, v[34:35]
	v_lshl_add_u64 v[2:3], v[2:3], 0, v[4:5]
	v_lshl_add_u64 v[4:5], v[6:7], 0, v[12:13]
	v_lshl_add_u64 v[6:7], v[8:9], 0, v[14:15]
	v_add_co_u32_e32 v8, vcc, s9, v10
	v_lshl_add_u64 v[16:17], s[84:85], 0, v[34:35]
	s_nop 0
	v_addc_co_u32_e32 v9, vcc, 0, v11, vcc
	s_waitcnt vmcnt(4)
	v_lshlrev_b64 v[36:37], 4, v[2:3]
	v_lshlrev_b64 v[40:41], 4, v[6:7]
	v_add_co_u32_e32 v6, vcc, s9, v16
	v_lshl_add_u64 v[10:11], s[82:83], 0, v[36:37]
	s_nop 0
	v_addc_co_u32_e32 v7, vcc, 0, v17, vcc
	v_add_co_u32_e32 v10, vcc, s9, v10
	v_lshl_add_u64 v[12:13], s[84:85], 0, v[36:37]
	s_nop 0
	v_addc_co_u32_e32 v11, vcc, 0, v11, vcc
	v_lshlrev_b64 v[38:39], 4, v[4:5]
	v_add_co_u32_e32 v16, vcc, s9, v12
	v_lshl_add_u64 v[14:15], s[82:83], 0, v[38:39]
	s_nop 0
	v_addc_co_u32_e32 v17, vcc, 0, v13, vcc
	v_add_co_u32_e32 v24, vcc, s9, v14
	v_lshl_add_u64 v[18:19], s[84:85], 0, v[38:39]
	s_nop 0
	v_addc_co_u32_e32 v25, vcc, 0, v15, vcc
	v_add_co_u32_e32 v26, vcc, s9, v18
	v_lshl_add_u64 v[20:21], s[82:83], 0, v[40:41]
	s_nop 0
	v_addc_co_u32_e32 v27, vcc, 0, v19, vcc
	v_add_co_u32_e32 v28, vcc, s9, v20
	v_lshl_add_u64 v[22:23], s[84:85], 0, v[40:41]
	s_nop 0
	v_addc_co_u32_e32 v29, vcc, 0, v21, vcc
	v_add_co_u32_e32 v30, vcc, s9, v22
	global_load_dwordx4 v[2:5], v[8:9], off nt
	s_nop 0
	v_addc_co_u32_e32 v31, vcc, 0, v23, vcc
	global_load_dwordx4 v[6:9], v[6:7], off nt
	s_nop 0
	global_load_dwordx4 v[10:13], v[10:11], off nt
	s_nop 0
	global_load_dwordx4 v[14:17], v[16:17], off nt
	s_nop 0
	global_load_dwordx4 v[18:21], v[24:25], off nt
	s_nop 0
	global_load_dwordx4 v[22:25], v[26:27], off nt
	s_nop 0
	global_load_dwordx4 v[26:29], v[28:29], off nt
	s_nop 0
	global_load_dwordx4 v[30:33], v[30:31], off nt
	v_add_u32_e32 v0, s6, v0
	v_cmp_lt_i32_e32 vcc, s10, v0
	s_or_b64 s[2:3], vcc, s[2:3]
	v_lshl_add_u64 v[42:43], s[70:71], 0, v[34:35]
	v_lshl_add_u64 v[34:35], s[66:67], 0, v[34:35]
	v_lshl_add_u64 v[44:45], s[70:71], 0, v[36:37]
	v_lshl_add_u64 v[36:37], s[66:67], 0, v[36:37]
	v_lshl_add_u64 v[46:47], s[70:71], 0, v[38:39]
	v_lshl_add_u64 v[38:39], s[66:67], 0, v[38:39]
	v_lshl_add_u64 v[48:49], s[70:71], 0, v[40:41]
	v_lshl_add_u64 v[40:41], s[66:67], 0, v[40:41]
	s_waitcnt vmcnt(7)
	global_store_dwordx4 v[42:43], v[2:5], off nt
	s_waitcnt vmcnt(7)
	global_store_dwordx4 v[34:35], v[6:9], off nt
	s_waitcnt vmcnt(7)
	global_store_dwordx4 v[44:45], v[10:13], off nt
	s_waitcnt vmcnt(7)
	global_store_dwordx4 v[36:37], v[14:17], off nt
	s_waitcnt vmcnt(7)
	global_store_dwordx4 v[46:47], v[18:21], off nt
	s_waitcnt vmcnt(7)
	global_store_dwordx4 v[38:39], v[22:25], off nt
	s_waitcnt vmcnt(7)
	global_store_dwordx4 v[48:49], v[26:29], off nt
	s_waitcnt vmcnt(7)
	global_store_dwordx4 v[40:41], v[30:33], off nt
	s_andn2_b64 exec, exec, s[2:3]
	s_cbranch_execnz .LBB0_663

.LBB0_1030:
	s_add_u32 s42, s24, 0x1e04000
	s_addc_u32 s43, s25, 0
	s_add_i32 s5, s26, -4
	s_cmp_gt_i32 s88, 3
	s_cselect_b32 s5, s5, 0
	s_lshl_b32 s44, s0, 6
	s_lshl_b32 s7, s0, 13
	s_lshl_b32 s0, s1, 5
	s_and_b32 s45, s0, 0x60
	s_lshl_b32 s14, s45, 7
	s_add_u32 s10, s24, 0x1c20000
	s_mov_b64 s[12:13], 0x80
	s_addc_u32 s11, s25, 0
	s_add_i32 m0, s36, 0x18000
	v_lshl_add_u64 v[6:7], v[6:7], 0, s[12:13]
	s_waitcnt vmcnt(2)
	s_barrier
	global_load_lds_dwordx4 v[6:7], off
	v_lshl_add_u64 v[4:5], v[4:5], 0, s[12:13]
	s_add_i32 m0, s36, 0x1a000
	s_add_i32 s46, s36, 0x8000
	s_add_i32 s47, s36, 0xa000
	global_load_lds_dwordx4 v[4:5], off
	v_lshl_add_u64 v[2:3], v[2:3], 0, s[12:13]
	s_mov_b32 m0, s46
	s_add_u32 s0, s34, 0xb0080
	global_load_lds_dwordx4 v[2:3], off
	v_lshl_add_u64 v[0:1], v[0:1], 0, s[12:13]
	s_mov_b32 m0, s47
	s_addc_u32 s1, s35, 0
	global_load_lds_dwordx4 v[0:1], off
	s_add_i32 m0, s36, 0x1c000
	v_lshl_add_u64 v[0:1], s[0:1], 0, v[194:195]
	global_load_lds_dwordx4 v[0:1], off
	v_lshl_add_u64 v[0:1], s[0:1], 0, v[198:199]
	s_add_i32 m0, s36, 0x1e000
	v_bfe_u32 v227, v8, 4, 2
	global_load_lds_dwordx4 v[0:1], off
	v_and_b32_e32 v226, 15, v8
	v_lshlrev_b32_e32 v0, 4, v227
	v_lshlrev_b32_e32 v1, 2, v8
	v_lshl_or_b32 v0, v226, 6, v0
	v_and_b32_e32 v1, 32, v1
	s_cmpk_lt_u32 s6, 0x100
	v_bitop3_b32 v2, v0, s7, v1 bitop3:0xde
	v_bitop3_b32 v228, v0, s14, v1 bitop3:0xde
	s_cselect_b64 s[14:15], -1, 0
	v_and_b32_e32 v0, 63, v222
	s_cmp_gt_i32 s5, 0
	v_cmp_eq_u32_e64 s[0:1], 0, v0
	s_cselect_b64 s[6:7], -1, 0
	s_addk_i32 s64, 0xe000
	v_or_b32_e32 v0, 0x39f800, v222
	v_add_u32_e32 v229, s64, v0
	s_mov_b32 s16, 0x7f8000
	v_cmp_gt_i32_e32 vcc, s16, v229
	s_lshl_b32 s48, s5, 11
	v_lshrrev_b32_e32 v1, 1, v9
	v_mul_lo_u32 v0, v11, s4
	s_mov_b32 s5, 0xb000
	s_and_b64 s[16:17], s[6:7], vcc
	v_mad_u64_u32 v[0:1], s[6:7], v1, s5, v[0:1]
	v_or_b32_e32 v0, v0, v10
	s_mov_b64 s[18:19], 0xb0080
	v_add_lshl_u32 v0, v0, v12, 1
	v_mov_b32_e32 v1, v195
	v_lshl_add_u64 v[200:201], v[0:1], 0, s[18:19]
	v_lshrrev_b32_e32 v1, 1, v13
	v_mul_lo_u32 v0, v14, s4
	v_mad_u64_u32 v[0:1], s[4:5], v1, s5, v[0:1]
	s_waitcnt vmcnt(6)
	v_or_b32_e32 v0, v0, v15
	v_add_lshl_u32 v0, v0, v16, 1
	v_mov_b32_e32 v1, v195
	s_add_i32 s49, 0, 0x10000
	s_add_i32 s50, 0, 0x14000
	v_readlane_b32 s64, v247, 11
	v_lshl_add_u64 v[202:203], v[0:1], 0, s[18:19]
	v_mov_b64_e32 v[204:205], 0x104
	v_mov_b64_e32 v[206:207], 0x103
	v_add_u32_e32 v230, s49, v228
	v_add_u32_e32 v231, s50, v228
	v_add_u32_e32 v232, 0, v2
	s_movk_i32 s51, 0x3fff
	v_mbcnt_hi_u32_b32 v233, -1, v223
	s_mov_b32 s52, 0x80808081
	s_mov_b32 s53, 0xfffc0400
	s_mov_b32 s54, 0x7f7fff
	v_mov_b32_e32 v234, 0x358637bd
	v_readlane_b32 s65, v247, 12
	s_barrier
	s_branch .LBB0_1033
